# v53 plus fox skip-bound loads merged into one round trip, plus one static s_setprio 1 for waves 4..7 during the attention phase
# speedup vs baseline: 1.0020x; 1.0020x over previous
; #define PH(k) (IN(k) && ((MK_MASK >> (k)) & 1))
; #define REPS(k) for (int rep_ = 0; rep_ < (((MK_REP_MASK) >> (k)) & 1) + 1; ++rep_)
; __global__ void __launch_bounds__(NWAVES * 64, 2) mk_fwd(Params P) {
;     ...
;     if (PH(2)) REPS(2) {
;         for (int p = vcu; p < 1024; p += G) {
;             const int pp = p & 511, bh = pp >> 3, s = pp & 7, b = bh >> 3, hm = bh & 7;
;     ...
;             if (rep_ == 1 && !((MK_REP_ATT) & (p < 512 ? 1 : 2))) continue;
;     ...
;             for (int hh = 0; hh < 2; ++hh) {
;                 const int qb = hh ? s : 15 - s;
.LBB0_512:
	s_cmp_lt_i32 s74, 3
	s_cselect_b64 s[2:3], -1, 0
	s_and_b64 s[0:1], s[2:3], s[0:1]
	v_writelane_b32 v254, s0, 40
	s_andn2_b64 vcc, exec, s[0:1]
	s_nop 0
	v_writelane_b32 v254, s1, 41
	s_cbranch_vccnz .LBB0_747
	s_cmp_lt_u32 s93, 256
	s_cbranch_scc1 .Lprio_skip2
	s_setprio 1
.Lprio_skip2:
	s_cmpk_gt_i32 s95, 0x3ff
	s_cbranch_scc1 .LBB0_747
	v_writelane_b32 v254, s92, 42
	v_writelane_b32 v254, s90, 43
	s_add_u32 s0, s72, 0x300000
	s_mov_b32 s24, 0xfffa0000
	v_writelane_b32 v254, s91, 44
	v_writelane_b32 v254, s88, 45
	s_waitcnt lgkmcnt(0)
	v_mov_b32_e32 v1, 0
	s_mov_b32 s64, 0xf800000
	v_writelane_b32 v254, s89, 46
	v_writelane_b32 v254, s0, 47
	s_addc_u32 s0, s73, 0
	v_writelane_b32 v254, s0, 48
	s_add_u32 s0, s72, 0x1bf00000
	v_writelane_b32 v254, s0, 49
	s_addc_u32 s0, s73, 0
	v_writelane_b32 v254, s0, 50
	s_add_u32 s0, s72, 0xd800c00
	v_writelane_b32 v254, s0, 51
	s_addc_u32 s0, s73, 0
	v_writelane_b32 v254, s0, 52
	s_add_u32 s0, s72, 0xd801000
	v_writelane_b32 v254, s0, 53
	s_addc_u32 s0, s73, 0
	v_writelane_b32 v254, s0, 54
	s_add_u32 s0, s72, 0xd801400
	v_writelane_b32 v254, s0, 55
	s_addc_u32 s0, s73, 0
	v_writelane_b32 v254, s0, 56
	s_add_u32 s0, s72, 0x7800800
	v_writelane_b32 v254, s0, 57
	s_addc_u32 s0, s73, 0
	v_writelane_b32 v254, s0, 58
	s_and_b32 s94, s93, 0xffffffc0
	v_writelane_b32 v254, s93, 59
	s_add_u32 s0, s72, 0x300400
	v_writelane_b32 v254, s0, 60
	s_addc_u32 s0, s73, 0
	v_writelane_b32 v254, s0, 61
	s_add_u32 s0, s72, 0xd800000
	v_writelane_b32 v254, s0, 62
	s_addc_u32 s0, s73, 0
	v_writelane_b32 v254, s0, 63
	s_add_u32 s0, s72, 0xd800400
	v_writelane_b32 v255, s0, 0
	s_addc_u32 s0, s73, 0
	v_writelane_b32 v255, s0, 1
	s_add_u32 s0, s72, 0xd800800
	v_writelane_b32 v255, s0, 2
	s_addc_u32 s0, s73, 0
	v_writelane_b32 v255, s0, 3
	s_add_u32 s0, s72, 0x7800000
	v_writelane_b32 v255, s0, 4
	s_addc_u32 s0, s73, 0
	v_writelane_b32 v255, s0, 5
	s_lshl_b32 s0, s87, 10
	v_writelane_b32 v255, s87, 6
	s_add_i32 s62, s0, 0
	v_writelane_b32 v255, s95, 7
	s_add_i32 s62, s62, 0x14800
	s_lshl_b32 s63, s87, 8
	v_mov_b32_e32 v213, 0x260
	s_movk_i32 s65, 0x1800
	s_movk_i32 s66, 0xc00
	s_movk_i32 s67, 0x6000
	s_mov_b64 s[14:15], 0x60000
	s_mov_b64 s[16:17], 0xc0000
	s_movk_i32 s93, 0x4000
	s_mov_b64 s[18:19], 0x120000
	s_mov_b64 s[22:23], 0x1e0000
	s_add_i32 s3, 0, 0x14a00
	s_mov_b32 s25, -1
	s_mov_b32 s77, 0x41000000
	s_add_i32 s96, 0, 0x14900
	s_mov_b64 s[26:27], 0x180000
	s_mov_b32 s97, 0xc000
	s_mov_b32 s81, 0x41800000
	s_mov_b64 s[42:43], 0xc000
	s_mov_b64 s[44:45], 0x12000
	v_mov_b32_e32 v224, 0xff800000
	v_writelane_b32 v255, s82, 8
	s_branch .LBB0_516

; #define SEAM(k) do { if (IN(k) && IN((k) + 1)) { xcd_barrier(bar, wave == 0 && mk_lane() == 0); } } while (0)
; __device__ __forceinline__ void xcd_barrier(const XcdBarrier& b, bool leader) {
;     asm volatile("s_waitcnt vmcnt(0)" ::: "memory");
;     __syncthreads();
;     if (leader) {
;         unsigned* bar = b.bar;
;         __builtin_amdgcn_s_waitcnt(0);
;         unsigned nloc = b.st[0], nx = b.st[1];
;         if (nloc == 0u) { xcd_barrier_complete(bar, b.x, nloc, nx); b.st[0] = nloc; b.st[1] = nx; }
; __global__ void __launch_bounds__(NWAVES * 64, 2) mk_fwd(Params P) {
;     ...
;     }
;     SEAM(2);
.LBB0_747:
	s_setprio 0
	s_cmp_gt_i32 s75, 3
	v_readlane_b32 s2, v254, 40
	s_cselect_b64 s[0:1], -1, 0
	v_readlane_b32 s3, v254, 41
	s_and_b64 s[2:3], s[2:3], s[0:1]
	s_andn2_b64 vcc, exec, s[2:3]
	s_cbranch_vccnz .LBB0_799
	v_readlane_b32 s2, v254, 4
	v_readlane_b32 s3, v254, 5
	s_and_b64 vcc, exec, s[2:3]
	s_mov_b64 s[6:7], 0
	s_cbranch_vccnz .LBB0_750
	v_mov_b32_e32 v0, v212
	s_nop 0
	v_cmp_eq_u32_e32 vcc, 0, v0
	s_and_b64 s[6:7], vcc, exec
